# row_pass: mode 0 and mode 1 without XN also software-pipelined
# baseline (speedup 1.0000x reference)
.LBB0_127:
	v_readlane_b32 s18, v252, 0
	v_readlane_b32 s20, v252, 51
	v_readlane_b32 s19, v252, 1
	v_readlane_b32 s21, v252, 52
	s_mov_b64 s[4:5], s[18:19]
	s_mov_b64 s[30:31], s[18:19]
	v_mov_b32_e32 v0, v162
	s_andn2_b64 vcc, exec, s[20:21]
	s_cbranch_vccnz .LBB0_150
	s_xor_b64 s[20:21], s[6:7], -1
	v_readlane_b32 s29, v251, 62
	s_cmp_lg_u32 s29, 11
	s_cselect_b64 s[34:35], -1, 0
	s_cmp_eq_u32 s29, 8
	s_cselect_b64 s[36:37], -1, 0
	s_and_b64 s[38:39], s[36:37], exec
	s_cselect_b32 s23, 38, 41
	s_cmp_lg_u32 s29, 5
	s_cselect_b32 s23, s23, 33
	s_lshl_b32 s23, s23, 3
	s_load_dwordx2 s[4:5], s[4:5], s23 offset:0x0
	s_nop 0
	s_load_dwordx2 s[40:41], s[30:31], 0x158
	s_xor_b64 s[30:31], s[64:65], -1
	s_or_b64 s[30:31], s[30:31], s[34:35]
	s_and_b64 s[34:35], s[64:65], exec
	s_cselect_b32 s23, 0x1000, 0
	s_waitcnt lgkmcnt(0)
	s_add_u32 s4, s4, s23
	s_load_dwordx4 s[60:63], s[18:19], 0x150
	v_lshlrev_b32_e32 v18, 2, v0
	s_addc_u32 s5, s5, 0
	v_ashrrev_i32_e32 v19, 31, v18
	s_and_b64 s[6:7], s[6:7], s[36:37]
	s_waitcnt vmcnt(0)
	v_lshlrev_b64 v[2:3], 2, v[18:19]
	s_xor_b64 s[34:35], s[6:7], -1
	v_lshl_add_u64 v[20:21], s[4:5], 0, v[2:3]
	s_and_b64 s[4:5], s[64:65], exec
	v_readlane_b32 s5, v251, 26
	s_cselect_b32 s23, 0x80000, 0
	s_cselect_b32 s4, 0x1000000, 0
	s_waitcnt lgkmcnt(0)
	s_add_u32 s36, s62, s5
	v_readlane_b32 s5, v251, 27
	s_addc_u32 s37, s63, s5
	v_readlane_b32 s38, v251, 45
	v_readlane_b32 s39, v251, 46
	s_add_u32 s29, s38, s4
	s_addc_u32 s59, s39, 0
	v_readlane_b32 s4, v251, 51
	v_readlane_b32 s5, v251, 52
	s_add_u32 s38, s62, s4
	s_addc_u32 s39, s63, s5
	s_add_u32 s40, s40, s4
	s_addc_u32 s41, s41, s5
	v_readlane_b32 s4, v251, 30
	v_readlane_b32 s5, v251, 31
	s_add_u32 s4, s60, s4
	s_addc_u32 s5, s61, s5
	v_readlane_b32 s42, v251, 49
	v_lshlrev_b64 v[22:23], 1, v[18:19]
	v_lshl_add_u64 v[24:25], s[4:5], 0, v[2:3]
	v_readlane_b32 s43, v251, 50
	s_and_b64 vcc, exec, s[20:21]
	s_cbranch_vccnz .Lrdisp_m0
	s_and_b64 vcc, exec, s[30:31]
	s_cbranch_vccz .Lrdisp_noxn
	s_and_b64 vcc, exec, s[6:7]
	s_cbranch_vccnz .Lrq_entry
	s_branch .Lrp_entry
.Lrdisp_m0:
	s_and_b64 vcc, exec, s[30:31]
	s_cbranch_vccz .LBB0_131
	s_branch .Lr0_entry
.Lrdisp_noxn:
	s_and_b64 vcc, exec, s[6:7]
	s_cbranch_vccnz .LBB0_131
	s_branch .Lr3_entry

.Lr0_entry:
	s_load_dwordx2 s[100:101], s[18:19], 0x0
	s_load_dwordx2 s[44:45], s[18:19], 0x8
	s_waitcnt lgkmcnt(0)
	s_add_i32 s4, s42, 0xffffc000
	s_cmpk_lt_i32 s42, 0x4000
	s_cselect_b32 s4, s42, s4
	s_cselect_b32 s5, s43, 0
	s_cselect_b32 vcc_lo, s100, s44
	s_cselect_b32 vcc_hi, s101, s45
	s_lshl_b64 s[4:5], s[4:5], 12
	s_add_u32 s4, vcc_lo, s4
	s_addc_u32 s5, vcc_hi, s5
	v_lshl_add_u64 v[2:3], v[18:19], 2, s[4:5]
	global_load_dwordx4 v[14:17], v[2:3], off nt
	global_load_dwordx4 v[10:13], v[2:3], off offset:1024 nt
	global_load_dwordx4 v[6:9], v[2:3], off offset:2048 nt
	s_nop 0
	global_load_dwordx4 v[2:5], v[2:3], off offset:3072 nt
	v_mov_b32_e32 v130, v24
	v_mov_b32_e32 v131, v25
	v_lshl_add_u64 v[132:133], s[38:39], 0, v[22:23]
	v_readlane_b32 s4, v251, 53
	v_readlane_b32 s5, v251, 54
	s_add_u32 s42, s42, s4
	s_addc_u32 s43, s43, s5
	v_readlane_b32 s4, v251, 43
	v_readlane_b32 s5, v251, 44
	s_add_u32 s36, s36, s4
	s_addc_u32 s37, s37, s5
	v_readlane_b32 s4, v251, 47
	v_readlane_b32 s5, v251, 48
	s_add_u32 s29, s29, s4
	s_addc_u32 s59, s59, s5
	s_add_u32 s38, s38, s56
	s_addc_u32 s39, s39, s57
	s_add_u32 s40, s40, s56
	v_readlane_b32 s4, v251, 55
	s_addc_u32 s41, s41, s57
	v_readlane_b32 s5, v251, 56
	s_cmpk_gt_i32 s42, 0x41ff
	s_cselect_b32 s98, 0, 1
	s_nop 0
	v_lshl_add_u64 v[24:25], v[24:25], 0, s[4:5]
	global_load_dword v129, v[20:21], off
	global_load_dword v129, v[20:21], off
	global_load_dword v129, v[20:21], off
	global_load_dword v129, v[20:21], off
	global_load_dword v129, v[20:21], off
	global_load_dword v129, v[20:21], off
	global_load_dword v129, v[20:21], off
	global_load_dword v129, v[20:21], off
.Lr0_loop:
	s_cmp_eq_u32 s98, 0
	s_cbranch_scc1 .Lr0_tail1
	s_add_i32 s4, s42, 0xffffc000
	s_cmpk_lt_i32 s42, 0x4000
	s_cselect_b32 s4, s42, s4
	s_cselect_b32 s5, s43, 0
	s_cselect_b32 vcc_lo, s100, s44
	s_cselect_b32 vcc_hi, s101, s45
	s_lshl_b64 s[4:5], s[4:5], 12
	s_add_u32 s4, vcc_lo, s4
	s_addc_u32 s5, vcc_hi, s5
	v_lshl_add_u64 v[66:67], v[18:19], 2, s[4:5]
	global_load_dwordx4 v[78:81], v[66:67], off nt
	global_load_dwordx4 v[74:77], v[66:67], off offset:1024 nt
	global_load_dwordx4 v[70:73], v[66:67], off offset:2048 nt
	s_nop 0
	global_load_dwordx4 v[66:69], v[66:67], off offset:3072 nt
	v_mov_b32_e32 v134, v24
	v_mov_b32_e32 v135, v25
	v_lshl_add_u64 v[136:137], s[38:39], 0, v[22:23]
	v_readlane_b32 s4, v251, 53
	v_readlane_b32 s5, v251, 54
	s_add_u32 s42, s42, s4
	s_addc_u32 s43, s43, s5
	v_readlane_b32 s4, v251, 43
	v_readlane_b32 s5, v251, 44
	s_add_u32 s36, s36, s4
	s_addc_u32 s37, s37, s5
	v_readlane_b32 s4, v251, 47
	v_readlane_b32 s5, v251, 48
	s_add_u32 s29, s29, s4
	s_addc_u32 s59, s59, s5
	s_add_u32 s38, s38, s56
	s_addc_u32 s39, s39, s57
	s_add_u32 s40, s40, s56
	v_readlane_b32 s4, v251, 55
	s_addc_u32 s41, s41, s57
	v_readlane_b32 s5, v251, 56
	s_cmpk_gt_i32 s42, 0x41ff
	s_cselect_b32 s98, 0, 1
	s_nop 0
	v_lshl_add_u64 v[24:25], v[24:25], 0, s[4:5]
	v_mov_b32_e32 v26, 1.0
	s_waitcnt vmcnt(15)
	v_pk_mul_f32 v[26:27], v[14:15], v[14:15]
	s_waitcnt vmcnt(14)
	v_pk_mul_f32 v[28:29], v[10:11], v[10:11]
	v_pk_mul_f32 v[30:31], v[16:17], v[16:17]
	v_pk_mul_f32 v[32:33], v[12:13], v[12:13]
	v_mov_b32_e32 v34, v31
	v_mov_b32_e32 v35, v33
	v_mov_b32_e32 v31, v32
	v_mov_b32_e32 v32, v26
	v_mov_b32_e32 v33, v28
	v_mov_b32_e32 v28, v27
	v_pk_add_f32 v[26:27], v[32:33], v[28:29]
	s_waitcnt vmcnt(12)
	v_mov_b32_e32 v32, v2
	v_pk_add_f32 v[26:27], v[30:31], v[26:27]
	v_mov_b32_e32 v33, v6
	v_pk_add_f32 v[26:27], v[34:35], v[26:27]
	v_mov_b32_e32 v34, v3
	v_mov_b32_e32 v35, v7
	v_pk_mul_f32 v[34:35], v[34:35], v[34:35]
	v_mov_b32_e32 v30, v4
	v_mov_b32_e32 v31, v8
	v_pk_fma_f32 v[32:33], v[32:33], v[32:33], v[34:35]
	v_mov_b32_e32 v28, v5
	v_mov_b32_e32 v29, v9
	v_pk_fma_f32 v[30:31], v[30:31], v[30:31], v[32:33]
	v_add_f32_e32 v0, v26, v27
	v_pk_fma_f32 v[28:29], v[28:29], v[28:29], v[30:31]
	s_nop 0
	v_add_f32_e32 v0, v29, v0
	v_add_f32_e32 v0, v28, v0
	ds_bpermute_b32 v26, v163, v0
	s_waitcnt lgkmcnt(0)
	v_add_f32_e32 v0, v0, v26
	ds_bpermute_b32 v26, v164, v0
	s_waitcnt lgkmcnt(0)
	v_add_f32_e32 v0, v0, v26
	ds_bpermute_b32 v26, v165, v0
	s_waitcnt lgkmcnt(0)
	v_add_f32_e32 v0, v0, v26
	ds_bpermute_b32 v26, v166, v0
	s_waitcnt lgkmcnt(0)
	v_add_f32_e32 v0, v0, v26
	ds_bpermute_b32 v26, v167, v0
	s_waitcnt lgkmcnt(0)
	v_add_f32_e32 v0, v0, v26
	ds_bpermute_b32 v26, v168, v0
	s_waitcnt lgkmcnt(0)
	v_add_f32_e32 v0, v0, v26
	v_fmamk_f32 v0, v0, 0x3a800000, v169
	v_mul_f32_e32 v26, 0x4b800000, v0
	v_cmp_gt_f32_e32 vcc, s74, v0
	s_nop 1
	v_cndmask_b32_e32 v0, v0, v26, vcc
	v_rsq_f32_e32 v0, v0
	s_nop 0
	v_mul_f32_e32 v26, 0x45800000, v0
	v_cndmask_b32_e32 v26, v0, v26, vcc
	v_mov_b32_e32 v28, v132
	v_mov_b32_e32 v29, v133
	v_mov_b32_e32 v27, v26
	s_waitcnt vmcnt(15)
	global_store_dwordx4 v[130:131], v[14:17], off offset:-3072 nt
	v_mov_b32_e32 v30, v26
	v_mov_b32_e32 v31, v26
	v_pk_mul_f32 v[16:17], v[16:17], v[30:31]
	v_pk_mul_f32 v[14:15], v[14:15], v[26:27]
	s_nop 0
	v_cvt_pk_bf16_f32 v14, v14, v15
	v_cvt_pk_bf16_f32 v15, v16, v17
	v_add_co_u32_e32 v16, vcc, 0x2b00000, v28
	s_nop 1
	v_addc_co_u32_e32 v17, vcc, 0, v29, vcc
	global_store_dwordx2 v[16:17], v[14:15], off
	s_waitcnt vmcnt(16)
	global_store_dwordx4 v[130:131], v[10:13], off offset:-2048 nt
	v_pk_mul_f32 v[14:15], v[12:13], v[30:31]
	v_pk_mul_f32 v[30:31], v[10:11], v[26:27]
	s_nop 0
	v_cvt_pk_bf16_f32 v30, v30, v31
	v_cvt_pk_bf16_f32 v31, v14, v15
	global_store_dwordx2 v[16:17], v[30:31], off offset:512
	s_waitcnt vmcnt(14)
	global_store_dwordx4 v[130:131], v[6:9], off offset:-1024 nt
	v_mov_b32_e32 v10, v26
	v_mov_b32_e32 v11, v26
	v_pk_mul_f32 v[8:9], v[8:9], v[10:11]
	v_pk_mul_f32 v[6:7], v[6:7], v[26:27]
	s_nop 0
	v_cvt_pk_bf16_f32 v6, v6, v7
	v_cvt_pk_bf16_f32 v7, v8, v9
	v_add_co_u32_e32 v8, vcc, 0x2b00000, v28
	s_nop 1
	v_addc_co_u32_e32 v9, vcc, 0, v29, vcc
	global_store_dwordx2 v[8:9], v[6:7], off offset:1024
	s_waitcnt vmcnt(15)
	global_store_dwordx4 v[130:131], v[2:5], off nt
	v_pk_mul_f32 v[6:7], v[4:5], v[10:11]
	v_pk_mul_f32 v[10:11], v[2:3], v[26:27]
	s_nop 0
	v_cvt_pk_bf16_f32 v10, v10, v11
	v_cvt_pk_bf16_f32 v11, v6, v7
	global_store_dwordx2 v[8:9], v[10:11], off offset:1536
	s_cmp_eq_u32 s98, 0
	s_cbranch_scc1 .Lr0_tail2
	s_add_i32 s4, s42, 0xffffc000
	s_cmpk_lt_i32 s42, 0x4000
	s_cselect_b32 s4, s42, s4
	s_cselect_b32 s5, s43, 0
	s_cselect_b32 vcc_lo, s100, s44
	s_cselect_b32 vcc_hi, s101, s45
	s_lshl_b64 s[4:5], s[4:5], 12
	s_add_u32 s4, vcc_lo, s4
	s_addc_u32 s5, vcc_hi, s5
	v_lshl_add_u64 v[2:3], v[18:19], 2, s[4:5]
	global_load_dwordx4 v[14:17], v[2:3], off nt
	global_load_dwordx4 v[10:13], v[2:3], off offset:1024 nt
	global_load_dwordx4 v[6:9], v[2:3], off offset:2048 nt
	s_nop 0
	global_load_dwordx4 v[2:5], v[2:3], off offset:3072 nt
	v_mov_b32_e32 v130, v24
	v_mov_b32_e32 v131, v25
	v_lshl_add_u64 v[132:133], s[38:39], 0, v[22:23]
	v_readlane_b32 s4, v251, 53
	v_readlane_b32 s5, v251, 54
	s_add_u32 s42, s42, s4
	s_addc_u32 s43, s43, s5
	v_readlane_b32 s4, v251, 43
	v_readlane_b32 s5, v251, 44
	s_add_u32 s36, s36, s4
	s_addc_u32 s37, s37, s5
	v_readlane_b32 s4, v251, 47
	v_readlane_b32 s5, v251, 48
	s_add_u32 s29, s29, s4
	s_addc_u32 s59, s59, s5
	s_add_u32 s38, s38, s56
	s_addc_u32 s39, s39, s57
	s_add_u32 s40, s40, s56
	v_readlane_b32 s4, v251, 55
	s_addc_u32 s41, s41, s57
	v_readlane_b32 s5, v251, 56
	s_cmpk_gt_i32 s42, 0x41ff
	s_cselect_b32 s98, 0, 1
	s_nop 0
	v_lshl_add_u64 v[24:25], v[24:25], 0, s[4:5]
	v_mov_b32_e32 v90, 1.0
	s_waitcnt vmcnt(15)
	v_pk_mul_f32 v[90:91], v[78:79], v[78:79]
	s_waitcnt vmcnt(14)
	v_pk_mul_f32 v[92:93], v[74:75], v[74:75]
	v_pk_mul_f32 v[94:95], v[80:81], v[80:81]
	v_pk_mul_f32 v[96:97], v[76:77], v[76:77]
	v_mov_b32_e32 v98, v95
	v_mov_b32_e32 v99, v97
	v_mov_b32_e32 v95, v96
	v_mov_b32_e32 v96, v90
	v_mov_b32_e32 v97, v92
	v_mov_b32_e32 v92, v91
	v_pk_add_f32 v[90:91], v[96:97], v[92:93]
	s_waitcnt vmcnt(12)
	v_mov_b32_e32 v96, v66
	v_pk_add_f32 v[90:91], v[94:95], v[90:91]
	v_mov_b32_e32 v97, v70
	v_pk_add_f32 v[90:91], v[98:99], v[90:91]
	v_mov_b32_e32 v98, v67
	v_mov_b32_e32 v99, v71
	v_pk_mul_f32 v[98:99], v[98:99], v[98:99]
	v_mov_b32_e32 v94, v68
	v_mov_b32_e32 v95, v72
	v_pk_fma_f32 v[96:97], v[96:97], v[96:97], v[98:99]
	v_mov_b32_e32 v92, v69
	v_mov_b32_e32 v93, v73
	v_pk_fma_f32 v[94:95], v[94:95], v[94:95], v[96:97]
	v_add_f32_e32 v64, v90, v91
	v_pk_fma_f32 v[92:93], v[92:93], v[92:93], v[94:95]
	s_nop 0
	v_add_f32_e32 v64, v93, v64
	v_add_f32_e32 v64, v92, v64
	ds_bpermute_b32 v90, v163, v64
	s_waitcnt lgkmcnt(0)
	v_add_f32_e32 v64, v64, v90
	ds_bpermute_b32 v90, v164, v64
	s_waitcnt lgkmcnt(0)
	v_add_f32_e32 v64, v64, v90
	ds_bpermute_b32 v90, v165, v64
	s_waitcnt lgkmcnt(0)
	v_add_f32_e32 v64, v64, v90
	ds_bpermute_b32 v90, v166, v64
	s_waitcnt lgkmcnt(0)
	v_add_f32_e32 v64, v64, v90
	ds_bpermute_b32 v90, v167, v64
	s_waitcnt lgkmcnt(0)
	v_add_f32_e32 v64, v64, v90
	ds_bpermute_b32 v90, v168, v64
	s_waitcnt lgkmcnt(0)
	v_add_f32_e32 v64, v64, v90
	v_fmamk_f32 v64, v64, 0x3a800000, v169
	v_mul_f32_e32 v90, 0x4b800000, v64
	v_cmp_gt_f32_e32 vcc, s74, v64
	s_nop 1
	v_cndmask_b32_e32 v64, v64, v90, vcc
	v_rsq_f32_e32 v64, v64
	s_nop 0
	v_mul_f32_e32 v90, 0x45800000, v64
	v_cndmask_b32_e32 v90, v64, v90, vcc
	v_mov_b32_e32 v92, v136
	v_mov_b32_e32 v93, v137
	v_mov_b32_e32 v91, v90
	s_waitcnt vmcnt(15)
	global_store_dwordx4 v[134:135], v[78:81], off offset:-3072 nt
	v_mov_b32_e32 v94, v90
	v_mov_b32_e32 v95, v90
	v_pk_mul_f32 v[80:81], v[80:81], v[94:95]
	v_pk_mul_f32 v[78:79], v[78:79], v[90:91]
	s_nop 0
	v_cvt_pk_bf16_f32 v78, v78, v79
	v_cvt_pk_bf16_f32 v79, v80, v81
	v_add_co_u32_e32 v80, vcc, 0x2b00000, v92
	s_nop 1
	v_addc_co_u32_e32 v81, vcc, 0, v93, vcc
	global_store_dwordx2 v[80:81], v[78:79], off
	s_waitcnt vmcnt(16)
	global_store_dwordx4 v[134:135], v[74:77], off offset:-2048 nt
	v_pk_mul_f32 v[78:79], v[76:77], v[94:95]
	v_pk_mul_f32 v[94:95], v[74:75], v[90:91]
	s_nop 0
	v_cvt_pk_bf16_f32 v94, v94, v95
	v_cvt_pk_bf16_f32 v95, v78, v79
	global_store_dwordx2 v[80:81], v[94:95], off offset:512
	s_waitcnt vmcnt(14)
	global_store_dwordx4 v[134:135], v[70:73], off offset:-1024 nt
	v_mov_b32_e32 v74, v90
	v_mov_b32_e32 v75, v90
	v_pk_mul_f32 v[72:73], v[72:73], v[74:75]
	v_pk_mul_f32 v[70:71], v[70:71], v[90:91]
	s_nop 0
	v_cvt_pk_bf16_f32 v70, v70, v71
	v_cvt_pk_bf16_f32 v71, v72, v73
	v_add_co_u32_e32 v72, vcc, 0x2b00000, v92
	s_nop 1
	v_addc_co_u32_e32 v73, vcc, 0, v93, vcc
	global_store_dwordx2 v[72:73], v[70:71], off offset:1024
	s_waitcnt vmcnt(15)
	global_store_dwordx4 v[134:135], v[66:69], off nt
	v_pk_mul_f32 v[70:71], v[68:69], v[74:75]
	v_pk_mul_f32 v[74:75], v[66:67], v[90:91]
	s_nop 0
	v_cvt_pk_bf16_f32 v74, v74, v75
	v_cvt_pk_bf16_f32 v75, v70, v71
	global_store_dwordx2 v[72:73], v[74:75], off offset:1536
	s_branch .Lr0_loop
.Lr0_tail1:
	s_waitcnt vmcnt(0)
	v_mov_b32_e32 v26, 1.0
	s_waitcnt vmcnt(3)
	v_pk_mul_f32 v[26:27], v[14:15], v[14:15]
	s_waitcnt vmcnt(2)
	v_pk_mul_f32 v[28:29], v[10:11], v[10:11]
	v_pk_mul_f32 v[30:31], v[16:17], v[16:17]
	v_pk_mul_f32 v[32:33], v[12:13], v[12:13]
	v_mov_b32_e32 v34, v31
	v_mov_b32_e32 v35, v33
	v_mov_b32_e32 v31, v32
	v_mov_b32_e32 v32, v26
	v_mov_b32_e32 v33, v28
	v_mov_b32_e32 v28, v27
	v_pk_add_f32 v[26:27], v[32:33], v[28:29]
	s_waitcnt vmcnt(0)
	v_mov_b32_e32 v32, v2
	v_pk_add_f32 v[26:27], v[30:31], v[26:27]
	v_mov_b32_e32 v33, v6
	v_pk_add_f32 v[26:27], v[34:35], v[26:27]
	v_mov_b32_e32 v34, v3
	v_mov_b32_e32 v35, v7
	v_pk_mul_f32 v[34:35], v[34:35], v[34:35]
	v_mov_b32_e32 v30, v4
	v_mov_b32_e32 v31, v8
	v_pk_fma_f32 v[32:33], v[32:33], v[32:33], v[34:35]
	v_mov_b32_e32 v28, v5
	v_mov_b32_e32 v29, v9
	v_pk_fma_f32 v[30:31], v[30:31], v[30:31], v[32:33]
	v_add_f32_e32 v0, v26, v27
	v_pk_fma_f32 v[28:29], v[28:29], v[28:29], v[30:31]
	s_nop 0
	v_add_f32_e32 v0, v29, v0
	v_add_f32_e32 v0, v28, v0
	ds_bpermute_b32 v26, v163, v0
	s_waitcnt lgkmcnt(0)
	v_add_f32_e32 v0, v0, v26
	ds_bpermute_b32 v26, v164, v0
	s_waitcnt lgkmcnt(0)
	v_add_f32_e32 v0, v0, v26
	ds_bpermute_b32 v26, v165, v0
	s_waitcnt lgkmcnt(0)
	v_add_f32_e32 v0, v0, v26
	ds_bpermute_b32 v26, v166, v0
	s_waitcnt lgkmcnt(0)
	v_add_f32_e32 v0, v0, v26
	ds_bpermute_b32 v26, v167, v0
	s_waitcnt lgkmcnt(0)
	v_add_f32_e32 v0, v0, v26
	ds_bpermute_b32 v26, v168, v0
	s_waitcnt lgkmcnt(0)
	v_add_f32_e32 v0, v0, v26
	v_fmamk_f32 v0, v0, 0x3a800000, v169
	v_mul_f32_e32 v26, 0x4b800000, v0
	v_cmp_gt_f32_e32 vcc, s74, v0
	s_nop 1
	v_cndmask_b32_e32 v0, v0, v26, vcc
	v_rsq_f32_e32 v0, v0
	s_nop 0
	v_mul_f32_e32 v26, 0x45800000, v0
	v_cndmask_b32_e32 v26, v0, v26, vcc
	v_mov_b32_e32 v28, v132
	v_mov_b32_e32 v29, v133
	v_mov_b32_e32 v27, v26
	s_waitcnt vmcnt(3)
	global_store_dwordx4 v[130:131], v[14:17], off offset:-3072 nt
	v_mov_b32_e32 v30, v26
	v_mov_b32_e32 v31, v26
	v_pk_mul_f32 v[16:17], v[16:17], v[30:31]
	v_pk_mul_f32 v[14:15], v[14:15], v[26:27]
	s_nop 0
	v_cvt_pk_bf16_f32 v14, v14, v15
	v_cvt_pk_bf16_f32 v15, v16, v17
	v_add_co_u32_e32 v16, vcc, 0x2b00000, v28
	s_nop 1
	v_addc_co_u32_e32 v17, vcc, 0, v29, vcc
	global_store_dwordx2 v[16:17], v[14:15], off
	s_waitcnt vmcnt(4)
	global_store_dwordx4 v[130:131], v[10:13], off offset:-2048 nt
	v_pk_mul_f32 v[14:15], v[12:13], v[30:31]
	v_pk_mul_f32 v[30:31], v[10:11], v[26:27]
	s_nop 0
	v_cvt_pk_bf16_f32 v30, v30, v31
	v_cvt_pk_bf16_f32 v31, v14, v15
	global_store_dwordx2 v[16:17], v[30:31], off offset:512
	s_waitcnt vmcnt(2)
	global_store_dwordx4 v[130:131], v[6:9], off offset:-1024 nt
	v_mov_b32_e32 v10, v26
	v_mov_b32_e32 v11, v26
	v_pk_mul_f32 v[8:9], v[8:9], v[10:11]
	v_pk_mul_f32 v[6:7], v[6:7], v[26:27]
	s_nop 0
	v_cvt_pk_bf16_f32 v6, v6, v7
	v_cvt_pk_bf16_f32 v7, v8, v9
	v_add_co_u32_e32 v8, vcc, 0x2b00000, v28
	s_nop 1
	v_addc_co_u32_e32 v9, vcc, 0, v29, vcc
	global_store_dwordx2 v[8:9], v[6:7], off offset:1024
	s_waitcnt vmcnt(3)
	global_store_dwordx4 v[130:131], v[2:5], off nt
	v_pk_mul_f32 v[6:7], v[4:5], v[10:11]
	v_pk_mul_f32 v[10:11], v[2:3], v[26:27]
	s_nop 0
	v_cvt_pk_bf16_f32 v10, v10, v11
	v_cvt_pk_bf16_f32 v11, v6, v7
	global_store_dwordx2 v[8:9], v[10:11], off offset:1536
	s_branch .LBB0_150
.Lr0_tail2:
	s_waitcnt vmcnt(0)
	v_mov_b32_e32 v90, 1.0
	s_waitcnt vmcnt(3)
	v_pk_mul_f32 v[90:91], v[78:79], v[78:79]
	s_waitcnt vmcnt(2)
	v_pk_mul_f32 v[92:93], v[74:75], v[74:75]
	v_pk_mul_f32 v[94:95], v[80:81], v[80:81]
	v_pk_mul_f32 v[96:97], v[76:77], v[76:77]
	v_mov_b32_e32 v98, v95
	v_mov_b32_e32 v99, v97
	v_mov_b32_e32 v95, v96
	v_mov_b32_e32 v96, v90
	v_mov_b32_e32 v97, v92
	v_mov_b32_e32 v92, v91
	v_pk_add_f32 v[90:91], v[96:97], v[92:93]
	s_waitcnt vmcnt(0)
	v_mov_b32_e32 v96, v66
	v_pk_add_f32 v[90:91], v[94:95], v[90:91]
	v_mov_b32_e32 v97, v70
	v_pk_add_f32 v[90:91], v[98:99], v[90:91]
	v_mov_b32_e32 v98, v67
	v_mov_b32_e32 v99, v71
	v_pk_mul_f32 v[98:99], v[98:99], v[98:99]
	v_mov_b32_e32 v94, v68
	v_mov_b32_e32 v95, v72
	v_pk_fma_f32 v[96:97], v[96:97], v[96:97], v[98:99]
	v_mov_b32_e32 v92, v69
	v_mov_b32_e32 v93, v73
	v_pk_fma_f32 v[94:95], v[94:95], v[94:95], v[96:97]
	v_add_f32_e32 v64, v90, v91
	v_pk_fma_f32 v[92:93], v[92:93], v[92:93], v[94:95]
	s_nop 0
	v_add_f32_e32 v64, v93, v64
	v_add_f32_e32 v64, v92, v64
	ds_bpermute_b32 v90, v163, v64
	s_waitcnt lgkmcnt(0)
	v_add_f32_e32 v64, v64, v90
	ds_bpermute_b32 v90, v164, v64
	s_waitcnt lgkmcnt(0)
	v_add_f32_e32 v64, v64, v90
	ds_bpermute_b32 v90, v165, v64
	s_waitcnt lgkmcnt(0)
	v_add_f32_e32 v64, v64, v90
	ds_bpermute_b32 v90, v166, v64
	s_waitcnt lgkmcnt(0)
	v_add_f32_e32 v64, v64, v90
	ds_bpermute_b32 v90, v167, v64
	s_waitcnt lgkmcnt(0)
	v_add_f32_e32 v64, v64, v90
	ds_bpermute_b32 v90, v168, v64
	s_waitcnt lgkmcnt(0)
	v_add_f32_e32 v64, v64, v90
	v_fmamk_f32 v64, v64, 0x3a800000, v169
	v_mul_f32_e32 v90, 0x4b800000, v64
	v_cmp_gt_f32_e32 vcc, s74, v64
	s_nop 1
	v_cndmask_b32_e32 v64, v64, v90, vcc
	v_rsq_f32_e32 v64, v64
	s_nop 0
	v_mul_f32_e32 v90, 0x45800000, v64
	v_cndmask_b32_e32 v90, v64, v90, vcc
	v_mov_b32_e32 v92, v136
	v_mov_b32_e32 v93, v137
	v_mov_b32_e32 v91, v90
	s_waitcnt vmcnt(3)
	global_store_dwordx4 v[134:135], v[78:81], off offset:-3072 nt
	v_mov_b32_e32 v94, v90
	v_mov_b32_e32 v95, v90
	v_pk_mul_f32 v[80:81], v[80:81], v[94:95]
	v_pk_mul_f32 v[78:79], v[78:79], v[90:91]
	s_nop 0
	v_cvt_pk_bf16_f32 v78, v78, v79
	v_cvt_pk_bf16_f32 v79, v80, v81
	v_add_co_u32_e32 v80, vcc, 0x2b00000, v92
	s_nop 1
	v_addc_co_u32_e32 v81, vcc, 0, v93, vcc
	global_store_dwordx2 v[80:81], v[78:79], off
	s_waitcnt vmcnt(4)
	global_store_dwordx4 v[134:135], v[74:77], off offset:-2048 nt
	v_pk_mul_f32 v[78:79], v[76:77], v[94:95]
	v_pk_mul_f32 v[94:95], v[74:75], v[90:91]
	s_nop 0
	v_cvt_pk_bf16_f32 v94, v94, v95
	v_cvt_pk_bf16_f32 v95, v78, v79
	global_store_dwordx2 v[80:81], v[94:95], off offset:512
	s_waitcnt vmcnt(2)
	global_store_dwordx4 v[134:135], v[70:73], off offset:-1024 nt
	v_mov_b32_e32 v74, v90
	v_mov_b32_e32 v75, v90
	v_pk_mul_f32 v[72:73], v[72:73], v[74:75]
	v_pk_mul_f32 v[70:71], v[70:71], v[90:91]
	s_nop 0
	v_cvt_pk_bf16_f32 v70, v70, v71
	v_cvt_pk_bf16_f32 v71, v72, v73
	v_add_co_u32_e32 v72, vcc, 0x2b00000, v92
	s_nop 1
	v_addc_co_u32_e32 v73, vcc, 0, v93, vcc
	global_store_dwordx2 v[72:73], v[70:71], off offset:1024
	s_waitcnt vmcnt(3)
	global_store_dwordx4 v[134:135], v[66:69], off nt
	v_pk_mul_f32 v[70:71], v[68:69], v[74:75]
	v_pk_mul_f32 v[74:75], v[66:67], v[90:91]
	s_nop 0
	v_cvt_pk_bf16_f32 v74, v74, v75
	v_cvt_pk_bf16_f32 v75, v70, v71
	global_store_dwordx2 v[72:73], v[74:75], off offset:1536
	s_branch .LBB0_150

.Lr3_loop:
	s_cmp_eq_u32 s98, 0
	s_cbranch_scc1 .Lr3_tail1
	v_lshl_add_u64 v[66:67], s[40:41], 0, v[22:23]
	v_add_co_u32_e32 v66, vcc, 0x4c00000, v66
	s_nop 1
	v_addc_co_u32_e32 v67, vcc, 0, v67, vcc
	global_load_dwordx2 v[78:79], v[66:67], off offset:512 nt
	global_load_dwordx2 v[80:81], v[66:67], off offset:1024 nt
	global_load_dwordx2 v[110:111], v[66:67], off nt
	global_load_dwordx2 v[112:113], v[66:67], off offset:1536 nt
	s_nop 0
	global_load_dwordx4 v[66:69], v[20:21], off
	global_load_dwordx4 v[70:73], v[20:21], off offset:1024
	global_load_dwordx4 v[74:77], v[24:25], off offset:-3072 nt
	global_load_dwordx4 v[90:93], v[24:25], off offset:-2048 nt
	global_load_dwordx4 v[94:97], v[20:21], off offset:2048
	global_load_dwordx4 v[98:101], v[20:21], off offset:3072
	global_load_dwordx4 v[102:105], v[24:25], off offset:-1024 nt
	global_load_dwordx4 v[106:109], v[24:25], off nt
	v_mov_b32_e32 v134, v24
	v_mov_b32_e32 v135, v25
	v_lshl_add_u64 v[136:137], s[38:39], 0, v[22:23]
	v_readlane_b32 s4, v251, 53
	v_readlane_b32 s5, v251, 54
	s_add_u32 s42, s42, s4
	s_addc_u32 s43, s43, s5
	v_readlane_b32 s4, v251, 43
	v_readlane_b32 s5, v251, 44
	s_add_u32 s36, s36, s4
	s_addc_u32 s37, s37, s5
	v_readlane_b32 s4, v251, 47
	v_readlane_b32 s5, v251, 48
	s_add_u32 s29, s29, s4
	s_addc_u32 s59, s59, s5
	s_add_u32 s38, s38, s56
	s_addc_u32 s39, s39, s57
	s_add_u32 s40, s40, s56
	v_readlane_b32 s4, v251, 55
	s_addc_u32 s41, s41, s57
	v_readlane_b32 s5, v251, 56
	s_cmpk_gt_i32 s42, 0x41ff
	s_cselect_b32 s98, 0, 1
	s_nop 0
	v_lshl_add_u64 v[24:25], v[24:25], 0, s[4:5]
	s_waitcnt vmcnt(27)
	v_and_b32_e32 v53, 0xffff0000, v14
	v_lshlrev_b32_e32 v51, 16, v14
	s_waitcnt vmcnt(25)
	v_and_b32_e32 v52, 0xffff0000, v46
	v_lshlrev_b32_e32 v50, 16, v46
	v_lshlrev_b32_e32 v54, 16, v47
	v_and_b32_e32 v14, 0xffff0000, v47
	s_waitcnt vmcnt(24)
	v_lshlrev_b32_e32 v47, 16, v48
	v_lshlrev_b32_e32 v46, 16, v16
	v_and_b32_e32 v57, 0xffff0000, v48
	v_and_b32_e32 v56, 0xffff0000, v16
	v_lshlrev_b32_e32 v58, 16, v17
	v_and_b32_e32 v48, 0xffff0000, v17
	v_pk_mul_f32 v[16:17], v[52:53], v[52:53]
	v_lshlrev_b32_e32 v55, 16, v15
	v_pk_mul_f32 v[60:61], v[56:57], v[56:57]
	v_pk_fma_f32 v[16:17], v[50:51], v[50:51], v[16:17]
	v_and_b32_e32 v15, 0xffff0000, v15
	v_lshlrev_b32_e32 v59, 16, v49
	v_pk_fma_f32 v[60:61], v[46:47], v[46:47], v[60:61]
	v_pk_fma_f32 v[16:17], v[54:55], v[54:55], v[16:17]
	v_and_b32_e32 v49, 0xffff0000, v49
	v_pk_fma_f32 v[60:61], v[58:59], v[58:59], v[60:61]
	v_pk_fma_f32 v[16:17], v[14:15], v[14:15], v[16:17]
	v_pk_fma_f32 v[60:61], v[48:49], v[48:49], v[60:61]
	v_add_f32_e32 v0, v16, v17
	v_add_f32_e32 v0, v0, v60
	v_add_f32_e32 v0, v0, v61
	ds_bpermute_b32 v16, v163, v0
	v_mov_b32_e32 v61, v14
	v_mov_b32_e32 v60, v54
	v_mov_b32_e32 v62, v58
	v_mov_b32_e32 v63, v48
	s_waitcnt lgkmcnt(0)
	v_add_f32_e32 v0, v0, v16
	ds_bpermute_b32 v16, v164, v0
	v_mov_b32_e32 v48, v59
	s_waitcnt lgkmcnt(0)
	v_add_f32_e32 v0, v0, v16
	ds_bpermute_b32 v16, v165, v0
	s_waitcnt lgkmcnt(0)
	v_add_f32_e32 v0, v0, v16
	ds_bpermute_b32 v17, v166, v0
	v_mov_b32_e32 v16, v50
	s_waitcnt lgkmcnt(0)
	v_add_f32_e32 v0, v0, v17
	ds_bpermute_b32 v50, v167, v0
	v_mov_b32_e32 v17, v52
	v_mov_b32_e32 v52, v51
	v_mov_b32_e32 v51, v56
	v_mov_b32_e32 v56, v47
	s_waitcnt lgkmcnt(0)
	v_add_f32_e32 v0, v0, v50
	ds_bpermute_b32 v14, v168, v0
	v_mov_b32_e32 v50, v46
	s_waitcnt lgkmcnt(0)
	v_add_f32_e32 v0, v0, v14
	v_fmamk_f32 v0, v0, 0x3a800000, v169
	v_mul_f32_e32 v14, 0x4b800000, v0
	v_cmp_gt_f32_e32 vcc, s74, v0
	s_nop 1
	v_cndmask_b32_e32 v0, v0, v14, vcc
	v_rsq_f32_e32 v0, v0
	v_mov_b32_e32 v14, v55
	v_mul_f32_e32 v46, 0x45800000, v0
	v_cndmask_b32_e32 v0, v0, v46, vcc
	v_pk_mul_f32 v[46:47], v[16:17], v[0:1] op_sel_hi:[1,0]
	v_pk_mul_f32 v[16:17], v[60:61], v[0:1] op_sel_hi:[1,0]
	v_pk_mul_f32 v[52:53], v[52:53], v[0:1] op_sel_hi:[1,0]
	v_pk_mul_f32 v[54:55], v[14:15], v[0:1] op_sel_hi:[1,0]
	v_pk_mul_f32 v[50:51], v[50:51], v[0:1] op_sel_hi:[1,0]
	v_pk_mul_f32 v[58:59], v[62:63], v[0:1] op_sel_hi:[1,0]
	v_pk_mul_f32 v[56:57], v[56:57], v[0:1] op_sel_hi:[1,0]
	v_pk_mul_f32 v[48:49], v[48:49], v[0:1] op_sel_hi:[1,0]
	s_waitcnt vmcnt(21)
	v_pk_fma_f32 v[16:17], v[4:5], v[16:17], v[12:13]
	v_pk_fma_f32 v[14:15], v[2:3], v[46:47], v[10:11]
	s_waitcnt vmcnt(20)
	v_pk_fma_f32 v[12:13], v[8:9], v[54:55], v[28:29]
	v_pk_fma_f32 v[10:11], v[6:7], v[52:53], v[26:27]
	s_waitcnt vmcnt(17)
	v_pk_fma_f32 v[8:9], v[32:33], v[58:59], v[40:41]
	v_pk_fma_f32 v[6:7], v[30:31], v[50:51], v[38:39]
	s_waitcnt vmcnt(16)
	v_pk_fma_f32 v[4:5], v[36:37], v[48:49], v[44:45]
	v_pk_fma_f32 v[2:3], v[34:35], v[56:57], v[42:43]
	v_mov_b32_e32 v26, 1.0
	s_waitcnt vmcnt(19)
	v_pk_mul_f32 v[26:27], v[14:15], v[14:15]
	s_waitcnt vmcnt(18)
	v_pk_mul_f32 v[28:29], v[10:11], v[10:11]
	v_pk_mul_f32 v[30:31], v[16:17], v[16:17]
	v_pk_mul_f32 v[32:33], v[12:13], v[12:13]
	v_mov_b32_e32 v34, v31
	v_mov_b32_e32 v35, v33
	v_mov_b32_e32 v31, v32
	v_mov_b32_e32 v32, v26
	v_mov_b32_e32 v33, v28
	v_mov_b32_e32 v28, v27
	v_pk_add_f32 v[26:27], v[32:33], v[28:29]
	s_waitcnt vmcnt(16)
	v_mov_b32_e32 v32, v2
	v_pk_add_f32 v[26:27], v[30:31], v[26:27]
	v_mov_b32_e32 v33, v6
	v_pk_add_f32 v[26:27], v[34:35], v[26:27]
	v_mov_b32_e32 v34, v3
	v_mov_b32_e32 v35, v7
	v_pk_mul_f32 v[34:35], v[34:35], v[34:35]
	v_mov_b32_e32 v30, v4
	v_mov_b32_e32 v31, v8
	v_pk_fma_f32 v[32:33], v[32:33], v[32:33], v[34:35]
	v_mov_b32_e32 v28, v5
	v_mov_b32_e32 v29, v9
	v_pk_fma_f32 v[30:31], v[30:31], v[30:31], v[32:33]
	v_add_f32_e32 v0, v26, v27
	v_pk_fma_f32 v[28:29], v[28:29], v[28:29], v[30:31]
	s_nop 0
	v_add_f32_e32 v0, v29, v0
	v_add_f32_e32 v0, v28, v0
	ds_bpermute_b32 v26, v163, v0
	s_waitcnt lgkmcnt(0)
	v_add_f32_e32 v0, v0, v26
	ds_bpermute_b32 v26, v164, v0
	s_waitcnt lgkmcnt(0)
	v_add_f32_e32 v0, v0, v26
	ds_bpermute_b32 v26, v165, v0
	s_waitcnt lgkmcnt(0)
	v_add_f32_e32 v0, v0, v26
	ds_bpermute_b32 v26, v166, v0
	s_waitcnt lgkmcnt(0)
	v_add_f32_e32 v0, v0, v26
	ds_bpermute_b32 v26, v167, v0
	s_waitcnt lgkmcnt(0)
	v_add_f32_e32 v0, v0, v26
	ds_bpermute_b32 v26, v168, v0
	s_waitcnt lgkmcnt(0)
	v_add_f32_e32 v0, v0, v26
	v_fmamk_f32 v0, v0, 0x3a800000, v169
	v_mul_f32_e32 v26, 0x4b800000, v0
	v_cmp_gt_f32_e32 vcc, s74, v0
	s_nop 1
	v_cndmask_b32_e32 v0, v0, v26, vcc
	v_rsq_f32_e32 v0, v0
	s_nop 0
	v_mul_f32_e32 v26, 0x45800000, v0
	v_cndmask_b32_e32 v26, v0, v26, vcc
	v_mov_b32_e32 v27, v26
	s_waitcnt vmcnt(19)
	global_store_dwordx4 v[130:131], v[14:17], off offset:-3072 nt
	s_waitcnt vmcnt(19)
	global_store_dwordx4 v[130:131], v[10:13], off offset:-2048 nt
	s_waitcnt vmcnt(19)
	global_store_dwordx4 v[130:131], v[6:9], off offset:-1024 nt
	s_waitcnt vmcnt(18)
	global_store_dwordx4 v[130:131], v[2:5], off nt
	s_cmp_eq_u32 s98, 0
	s_cbranch_scc1 .Lr3_tail2
	v_lshl_add_u64 v[2:3], s[40:41], 0, v[22:23]
	v_add_co_u32_e32 v2, vcc, 0x4c00000, v2
	s_nop 1
	v_addc_co_u32_e32 v3, vcc, 0, v3, vcc
	global_load_dwordx2 v[14:15], v[2:3], off offset:512 nt
	global_load_dwordx2 v[16:17], v[2:3], off offset:1024 nt
	global_load_dwordx2 v[46:47], v[2:3], off nt
	global_load_dwordx2 v[48:49], v[2:3], off offset:1536 nt
	s_nop 0
	global_load_dwordx4 v[2:5], v[20:21], off
	global_load_dwordx4 v[6:9], v[20:21], off offset:1024
	global_load_dwordx4 v[10:13], v[24:25], off offset:-3072 nt
	global_load_dwordx4 v[26:29], v[24:25], off offset:-2048 nt
	global_load_dwordx4 v[30:33], v[20:21], off offset:2048
	global_load_dwordx4 v[34:37], v[20:21], off offset:3072
	global_load_dwordx4 v[38:41], v[24:25], off offset:-1024 nt
	global_load_dwordx4 v[42:45], v[24:25], off nt
	v_mov_b32_e32 v130, v24
	v_mov_b32_e32 v131, v25
	v_lshl_add_u64 v[132:133], s[38:39], 0, v[22:23]
	v_readlane_b32 s4, v251, 53
	v_readlane_b32 s5, v251, 54
	s_add_u32 s42, s42, s4
	s_addc_u32 s43, s43, s5
	v_readlane_b32 s4, v251, 43
	v_readlane_b32 s5, v251, 44
	s_add_u32 s36, s36, s4
	s_addc_u32 s37, s37, s5
	v_readlane_b32 s4, v251, 47
	v_readlane_b32 s5, v251, 48
	s_add_u32 s29, s29, s4
	s_addc_u32 s59, s59, s5
	s_add_u32 s38, s38, s56
	s_addc_u32 s39, s39, s57
	s_add_u32 s40, s40, s56
	v_readlane_b32 s4, v251, 55
	s_addc_u32 s41, s41, s57
	v_readlane_b32 s5, v251, 56
	s_cmpk_gt_i32 s42, 0x41ff
	s_cselect_b32 s98, 0, 1
	s_nop 0
	v_lshl_add_u64 v[24:25], v[24:25], 0, s[4:5]
	s_waitcnt vmcnt(27)
	v_and_b32_e32 v117, 0xffff0000, v78
	v_lshlrev_b32_e32 v115, 16, v78
	s_waitcnt vmcnt(25)
	v_and_b32_e32 v116, 0xffff0000, v110
	v_lshlrev_b32_e32 v114, 16, v110
	v_lshlrev_b32_e32 v118, 16, v111
	v_and_b32_e32 v78, 0xffff0000, v111
	s_waitcnt vmcnt(24)
	v_lshlrev_b32_e32 v111, 16, v112
	v_lshlrev_b32_e32 v110, 16, v80
	v_and_b32_e32 v121, 0xffff0000, v112
	v_and_b32_e32 v120, 0xffff0000, v80
	v_lshlrev_b32_e32 v122, 16, v81
	v_and_b32_e32 v112, 0xffff0000, v81
	v_pk_mul_f32 v[80:81], v[116:117], v[116:117]
	v_lshlrev_b32_e32 v119, 16, v79
	v_pk_mul_f32 v[124:125], v[120:121], v[120:121]
	v_pk_fma_f32 v[80:81], v[114:115], v[114:115], v[80:81]
	v_and_b32_e32 v79, 0xffff0000, v79
	v_lshlrev_b32_e32 v123, 16, v113
	v_pk_fma_f32 v[124:125], v[110:111], v[110:111], v[124:125]
	v_pk_fma_f32 v[80:81], v[118:119], v[118:119], v[80:81]
	v_and_b32_e32 v113, 0xffff0000, v113
	v_pk_fma_f32 v[124:125], v[122:123], v[122:123], v[124:125]
	v_pk_fma_f32 v[80:81], v[78:79], v[78:79], v[80:81]
	v_pk_fma_f32 v[124:125], v[112:113], v[112:113], v[124:125]
	v_add_f32_e32 v64, v80, v81
	v_add_f32_e32 v64, v64, v124
	v_add_f32_e32 v64, v64, v125
	ds_bpermute_b32 v80, v163, v64
	v_mov_b32_e32 v125, v78
	v_mov_b32_e32 v124, v118
	v_mov_b32_e32 v126, v122
	v_mov_b32_e32 v127, v112
	s_waitcnt lgkmcnt(0)
	v_add_f32_e32 v64, v64, v80
	ds_bpermute_b32 v80, v164, v64
	v_mov_b32_e32 v112, v123
	s_waitcnt lgkmcnt(0)
	v_add_f32_e32 v64, v64, v80
	ds_bpermute_b32 v80, v165, v64
	s_waitcnt lgkmcnt(0)
	v_add_f32_e32 v64, v64, v80
	ds_bpermute_b32 v81, v166, v64
	v_mov_b32_e32 v80, v114
	s_waitcnt lgkmcnt(0)
	v_add_f32_e32 v64, v64, v81
	ds_bpermute_b32 v114, v167, v64
	v_mov_b32_e32 v81, v116
	v_mov_b32_e32 v116, v115
	v_mov_b32_e32 v115, v120
	v_mov_b32_e32 v120, v111
	s_waitcnt lgkmcnt(0)
	v_add_f32_e32 v64, v64, v114
	ds_bpermute_b32 v78, v168, v64
	v_mov_b32_e32 v114, v110
	s_waitcnt lgkmcnt(0)
	v_add_f32_e32 v64, v64, v78
	v_fmamk_f32 v64, v64, 0x3a800000, v169
	v_mul_f32_e32 v78, 0x4b800000, v64
	v_cmp_gt_f32_e32 vcc, s74, v64
	s_nop 1
	v_cndmask_b32_e32 v64, v64, v78, vcc
	v_rsq_f32_e32 v64, v64
	v_mov_b32_e32 v78, v119
	v_mul_f32_e32 v110, 0x45800000, v64
	v_cndmask_b32_e32 v64, v64, v110, vcc
	v_pk_mul_f32 v[110:111], v[80:81], v[64:65] op_sel_hi:[1,0]
	v_pk_mul_f32 v[80:81], v[124:125], v[64:65] op_sel_hi:[1,0]
	v_pk_mul_f32 v[116:117], v[116:117], v[64:65] op_sel_hi:[1,0]
	v_pk_mul_f32 v[118:119], v[78:79], v[64:65] op_sel_hi:[1,0]
	v_pk_mul_f32 v[114:115], v[114:115], v[64:65] op_sel_hi:[1,0]
	v_pk_mul_f32 v[122:123], v[126:127], v[64:65] op_sel_hi:[1,0]
	v_pk_mul_f32 v[120:121], v[120:121], v[64:65] op_sel_hi:[1,0]
	v_pk_mul_f32 v[112:113], v[112:113], v[64:65] op_sel_hi:[1,0]
	s_waitcnt vmcnt(21)
	v_pk_fma_f32 v[80:81], v[68:69], v[80:81], v[76:77]
	v_pk_fma_f32 v[78:79], v[66:67], v[110:111], v[74:75]
	s_waitcnt vmcnt(20)
	v_pk_fma_f32 v[76:77], v[72:73], v[118:119], v[92:93]
	v_pk_fma_f32 v[74:75], v[70:71], v[116:117], v[90:91]
	s_waitcnt vmcnt(17)
	v_pk_fma_f32 v[72:73], v[96:97], v[122:123], v[104:105]
	v_pk_fma_f32 v[70:71], v[94:95], v[114:115], v[102:103]
	s_waitcnt vmcnt(16)
	v_pk_fma_f32 v[68:69], v[100:101], v[112:113], v[108:109]
	v_pk_fma_f32 v[66:67], v[98:99], v[120:121], v[106:107]
	v_mov_b32_e32 v90, 1.0
	s_waitcnt vmcnt(19)
	v_pk_mul_f32 v[90:91], v[78:79], v[78:79]
	s_waitcnt vmcnt(18)
	v_pk_mul_f32 v[92:93], v[74:75], v[74:75]
	v_pk_mul_f32 v[94:95], v[80:81], v[80:81]
	v_pk_mul_f32 v[96:97], v[76:77], v[76:77]
	v_mov_b32_e32 v98, v95
	v_mov_b32_e32 v99, v97
	v_mov_b32_e32 v95, v96
	v_mov_b32_e32 v96, v90
	v_mov_b32_e32 v97, v92
	v_mov_b32_e32 v92, v91
	v_pk_add_f32 v[90:91], v[96:97], v[92:93]
	s_waitcnt vmcnt(16)
	v_mov_b32_e32 v96, v66
	v_pk_add_f32 v[90:91], v[94:95], v[90:91]
	v_mov_b32_e32 v97, v70
	v_pk_add_f32 v[90:91], v[98:99], v[90:91]
	v_mov_b32_e32 v98, v67
	v_mov_b32_e32 v99, v71
	v_pk_mul_f32 v[98:99], v[98:99], v[98:99]
	v_mov_b32_e32 v94, v68
	v_mov_b32_e32 v95, v72
	v_pk_fma_f32 v[96:97], v[96:97], v[96:97], v[98:99]
	v_mov_b32_e32 v92, v69
	v_mov_b32_e32 v93, v73
	v_pk_fma_f32 v[94:95], v[94:95], v[94:95], v[96:97]
	v_add_f32_e32 v64, v90, v91
	v_pk_fma_f32 v[92:93], v[92:93], v[92:93], v[94:95]
	s_nop 0
	v_add_f32_e32 v64, v93, v64
	v_add_f32_e32 v64, v92, v64
	ds_bpermute_b32 v90, v163, v64
	s_waitcnt lgkmcnt(0)
	v_add_f32_e32 v64, v64, v90
	ds_bpermute_b32 v90, v164, v64
	s_waitcnt lgkmcnt(0)
	v_add_f32_e32 v64, v64, v90
	ds_bpermute_b32 v90, v165, v64
	s_waitcnt lgkmcnt(0)
	v_add_f32_e32 v64, v64, v90
	ds_bpermute_b32 v90, v166, v64
	s_waitcnt lgkmcnt(0)
	v_add_f32_e32 v64, v64, v90
	ds_bpermute_b32 v90, v167, v64
	s_waitcnt lgkmcnt(0)
	v_add_f32_e32 v64, v64, v90
	ds_bpermute_b32 v90, v168, v64
	s_waitcnt lgkmcnt(0)
	v_add_f32_e32 v64, v64, v90
	v_fmamk_f32 v64, v64, 0x3a800000, v169
	v_mul_f32_e32 v90, 0x4b800000, v64
	v_cmp_gt_f32_e32 vcc, s74, v64
	s_nop 1
	v_cndmask_b32_e32 v64, v64, v90, vcc
	v_rsq_f32_e32 v64, v64
	s_nop 0
	v_mul_f32_e32 v90, 0x45800000, v64
	v_cndmask_b32_e32 v90, v64, v90, vcc
	v_mov_b32_e32 v91, v90
	s_waitcnt vmcnt(19)
	global_store_dwordx4 v[134:135], v[78:81], off offset:-3072 nt
	s_waitcnt vmcnt(19)
	global_store_dwordx4 v[134:135], v[74:77], off offset:-2048 nt
	s_waitcnt vmcnt(19)
	global_store_dwordx4 v[134:135], v[70:73], off offset:-1024 nt
	s_waitcnt vmcnt(18)
	global_store_dwordx4 v[134:135], v[66:69], off nt
	s_branch .Lr3_loop
.Lr3_tail1:
	s_waitcnt vmcnt(0)
	s_waitcnt vmcnt(11)
	v_and_b32_e32 v53, 0xffff0000, v14
	v_lshlrev_b32_e32 v51, 16, v14
	s_waitcnt vmcnt(9)
	v_and_b32_e32 v52, 0xffff0000, v46
	v_lshlrev_b32_e32 v50, 16, v46
	v_lshlrev_b32_e32 v54, 16, v47
	v_and_b32_e32 v14, 0xffff0000, v47
	s_waitcnt vmcnt(8)
	v_lshlrev_b32_e32 v47, 16, v48
	v_lshlrev_b32_e32 v46, 16, v16
	v_and_b32_e32 v57, 0xffff0000, v48
	v_and_b32_e32 v56, 0xffff0000, v16
	v_lshlrev_b32_e32 v58, 16, v17
	v_and_b32_e32 v48, 0xffff0000, v17
	v_pk_mul_f32 v[16:17], v[52:53], v[52:53]
	v_lshlrev_b32_e32 v55, 16, v15
	v_pk_mul_f32 v[60:61], v[56:57], v[56:57]
	v_pk_fma_f32 v[16:17], v[50:51], v[50:51], v[16:17]
	v_and_b32_e32 v15, 0xffff0000, v15
	v_lshlrev_b32_e32 v59, 16, v49
	v_pk_fma_f32 v[60:61], v[46:47], v[46:47], v[60:61]
	v_pk_fma_f32 v[16:17], v[54:55], v[54:55], v[16:17]
	v_and_b32_e32 v49, 0xffff0000, v49
	v_pk_fma_f32 v[60:61], v[58:59], v[58:59], v[60:61]
	v_pk_fma_f32 v[16:17], v[14:15], v[14:15], v[16:17]
	v_pk_fma_f32 v[60:61], v[48:49], v[48:49], v[60:61]
	v_add_f32_e32 v0, v16, v17
	v_add_f32_e32 v0, v0, v60
	v_add_f32_e32 v0, v0, v61
	ds_bpermute_b32 v16, v163, v0
	v_mov_b32_e32 v61, v14
	v_mov_b32_e32 v60, v54
	v_mov_b32_e32 v62, v58
	v_mov_b32_e32 v63, v48
	s_waitcnt lgkmcnt(0)
	v_add_f32_e32 v0, v0, v16
	ds_bpermute_b32 v16, v164, v0
	v_mov_b32_e32 v48, v59
	s_waitcnt lgkmcnt(0)
	v_add_f32_e32 v0, v0, v16
	ds_bpermute_b32 v16, v165, v0
	s_waitcnt lgkmcnt(0)
	v_add_f32_e32 v0, v0, v16
	ds_bpermute_b32 v17, v166, v0
	v_mov_b32_e32 v16, v50
	s_waitcnt lgkmcnt(0)
	v_add_f32_e32 v0, v0, v17
	ds_bpermute_b32 v50, v167, v0
	v_mov_b32_e32 v17, v52
	v_mov_b32_e32 v52, v51
	v_mov_b32_e32 v51, v56
	v_mov_b32_e32 v56, v47
	s_waitcnt lgkmcnt(0)
	v_add_f32_e32 v0, v0, v50
	ds_bpermute_b32 v14, v168, v0
	v_mov_b32_e32 v50, v46
	s_waitcnt lgkmcnt(0)
	v_add_f32_e32 v0, v0, v14
	v_fmamk_f32 v0, v0, 0x3a800000, v169
	v_mul_f32_e32 v14, 0x4b800000, v0
	v_cmp_gt_f32_e32 vcc, s74, v0
	s_nop 1
	v_cndmask_b32_e32 v0, v0, v14, vcc
	v_rsq_f32_e32 v0, v0
	v_mov_b32_e32 v14, v55
	v_mul_f32_e32 v46, 0x45800000, v0
	v_cndmask_b32_e32 v0, v0, v46, vcc
	v_pk_mul_f32 v[46:47], v[16:17], v[0:1] op_sel_hi:[1,0]
	v_pk_mul_f32 v[16:17], v[60:61], v[0:1] op_sel_hi:[1,0]
	v_pk_mul_f32 v[52:53], v[52:53], v[0:1] op_sel_hi:[1,0]
	v_pk_mul_f32 v[54:55], v[14:15], v[0:1] op_sel_hi:[1,0]
	v_pk_mul_f32 v[50:51], v[50:51], v[0:1] op_sel_hi:[1,0]
	v_pk_mul_f32 v[58:59], v[62:63], v[0:1] op_sel_hi:[1,0]
	v_pk_mul_f32 v[56:57], v[56:57], v[0:1] op_sel_hi:[1,0]
	v_pk_mul_f32 v[48:49], v[48:49], v[0:1] op_sel_hi:[1,0]
	s_waitcnt vmcnt(5)
	v_pk_fma_f32 v[16:17], v[4:5], v[16:17], v[12:13]
	v_pk_fma_f32 v[14:15], v[2:3], v[46:47], v[10:11]
	s_waitcnt vmcnt(4)
	v_pk_fma_f32 v[12:13], v[8:9], v[54:55], v[28:29]
	v_pk_fma_f32 v[10:11], v[6:7], v[52:53], v[26:27]
	s_waitcnt vmcnt(1)
	v_pk_fma_f32 v[8:9], v[32:33], v[58:59], v[40:41]
	v_pk_fma_f32 v[6:7], v[30:31], v[50:51], v[38:39]
	s_waitcnt vmcnt(0)
	v_pk_fma_f32 v[4:5], v[36:37], v[48:49], v[44:45]
	v_pk_fma_f32 v[2:3], v[34:35], v[56:57], v[42:43]
	v_mov_b32_e32 v26, 1.0
	s_waitcnt vmcnt(3)
	v_pk_mul_f32 v[26:27], v[14:15], v[14:15]
	s_waitcnt vmcnt(2)
	v_pk_mul_f32 v[28:29], v[10:11], v[10:11]
	v_pk_mul_f32 v[30:31], v[16:17], v[16:17]
	v_pk_mul_f32 v[32:33], v[12:13], v[12:13]
	v_mov_b32_e32 v34, v31
	v_mov_b32_e32 v35, v33
	v_mov_b32_e32 v31, v32
	v_mov_b32_e32 v32, v26
	v_mov_b32_e32 v33, v28
	v_mov_b32_e32 v28, v27
	v_pk_add_f32 v[26:27], v[32:33], v[28:29]
	s_waitcnt vmcnt(0)
	v_mov_b32_e32 v32, v2
	v_pk_add_f32 v[26:27], v[30:31], v[26:27]
	v_mov_b32_e32 v33, v6
	v_pk_add_f32 v[26:27], v[34:35], v[26:27]
	v_mov_b32_e32 v34, v3
	v_mov_b32_e32 v35, v7
	v_pk_mul_f32 v[34:35], v[34:35], v[34:35]
	v_mov_b32_e32 v30, v4
	v_mov_b32_e32 v31, v8
	v_pk_fma_f32 v[32:33], v[32:33], v[32:33], v[34:35]
	v_mov_b32_e32 v28, v5
	v_mov_b32_e32 v29, v9
	v_pk_fma_f32 v[30:31], v[30:31], v[30:31], v[32:33]
	v_add_f32_e32 v0, v26, v27
	v_pk_fma_f32 v[28:29], v[28:29], v[28:29], v[30:31]
	s_nop 0
	v_add_f32_e32 v0, v29, v0
	v_add_f32_e32 v0, v28, v0
	ds_bpermute_b32 v26, v163, v0
	s_waitcnt lgkmcnt(0)
	v_add_f32_e32 v0, v0, v26
	ds_bpermute_b32 v26, v164, v0
	s_waitcnt lgkmcnt(0)
	v_add_f32_e32 v0, v0, v26
	ds_bpermute_b32 v26, v165, v0
	s_waitcnt lgkmcnt(0)
	v_add_f32_e32 v0, v0, v26
	ds_bpermute_b32 v26, v166, v0
	s_waitcnt lgkmcnt(0)
	v_add_f32_e32 v0, v0, v26
	ds_bpermute_b32 v26, v167, v0
	s_waitcnt lgkmcnt(0)
	v_add_f32_e32 v0, v0, v26
	ds_bpermute_b32 v26, v168, v0
	s_waitcnt lgkmcnt(0)
	v_add_f32_e32 v0, v0, v26
	v_fmamk_f32 v0, v0, 0x3a800000, v169
	v_mul_f32_e32 v26, 0x4b800000, v0
	v_cmp_gt_f32_e32 vcc, s74, v0
	s_nop 1
	v_cndmask_b32_e32 v0, v0, v26, vcc
	v_rsq_f32_e32 v0, v0
	s_nop 0
	v_mul_f32_e32 v26, 0x45800000, v0
	v_cndmask_b32_e32 v26, v0, v26, vcc
	v_mov_b32_e32 v27, v26
	s_waitcnt vmcnt(3)
	global_store_dwordx4 v[130:131], v[14:17], off offset:-3072 nt
	s_waitcnt vmcnt(3)
	global_store_dwordx4 v[130:131], v[10:13], off offset:-2048 nt
	s_waitcnt vmcnt(3)
	global_store_dwordx4 v[130:131], v[6:9], off offset:-1024 nt
	s_waitcnt vmcnt(2)
	global_store_dwordx4 v[130:131], v[2:5], off nt
	s_branch .LBB0_150
.Lr3_tail2:
	s_waitcnt vmcnt(0)
	s_waitcnt vmcnt(11)
	v_and_b32_e32 v117, 0xffff0000, v78
	v_lshlrev_b32_e32 v115, 16, v78
	s_waitcnt vmcnt(9)
	v_and_b32_e32 v116, 0xffff0000, v110
	v_lshlrev_b32_e32 v114, 16, v110
	v_lshlrev_b32_e32 v118, 16, v111
	v_and_b32_e32 v78, 0xffff0000, v111
	s_waitcnt vmcnt(8)
	v_lshlrev_b32_e32 v111, 16, v112
	v_lshlrev_b32_e32 v110, 16, v80
	v_and_b32_e32 v121, 0xffff0000, v112
	v_and_b32_e32 v120, 0xffff0000, v80
	v_lshlrev_b32_e32 v122, 16, v81
	v_and_b32_e32 v112, 0xffff0000, v81
	v_pk_mul_f32 v[80:81], v[116:117], v[116:117]
	v_lshlrev_b32_e32 v119, 16, v79
	v_pk_mul_f32 v[124:125], v[120:121], v[120:121]
	v_pk_fma_f32 v[80:81], v[114:115], v[114:115], v[80:81]
	v_and_b32_e32 v79, 0xffff0000, v79
	v_lshlrev_b32_e32 v123, 16, v113
	v_pk_fma_f32 v[124:125], v[110:111], v[110:111], v[124:125]
	v_pk_fma_f32 v[80:81], v[118:119], v[118:119], v[80:81]
	v_and_b32_e32 v113, 0xffff0000, v113
	v_pk_fma_f32 v[124:125], v[122:123], v[122:123], v[124:125]
	v_pk_fma_f32 v[80:81], v[78:79], v[78:79], v[80:81]
	v_pk_fma_f32 v[124:125], v[112:113], v[112:113], v[124:125]
	v_add_f32_e32 v64, v80, v81
	v_add_f32_e32 v64, v64, v124
	v_add_f32_e32 v64, v64, v125
	ds_bpermute_b32 v80, v163, v64
	v_mov_b32_e32 v125, v78
	v_mov_b32_e32 v124, v118
	v_mov_b32_e32 v126, v122
	v_mov_b32_e32 v127, v112
	s_waitcnt lgkmcnt(0)
	v_add_f32_e32 v64, v64, v80
	ds_bpermute_b32 v80, v164, v64
	v_mov_b32_e32 v112, v123
	s_waitcnt lgkmcnt(0)
	v_add_f32_e32 v64, v64, v80
	ds_bpermute_b32 v80, v165, v64
	s_waitcnt lgkmcnt(0)
	v_add_f32_e32 v64, v64, v80
	ds_bpermute_b32 v81, v166, v64
	v_mov_b32_e32 v80, v114
	s_waitcnt lgkmcnt(0)
	v_add_f32_e32 v64, v64, v81
	ds_bpermute_b32 v114, v167, v64
	v_mov_b32_e32 v81, v116
	v_mov_b32_e32 v116, v115
	v_mov_b32_e32 v115, v120
	v_mov_b32_e32 v120, v111
	s_waitcnt lgkmcnt(0)
	v_add_f32_e32 v64, v64, v114
	ds_bpermute_b32 v78, v168, v64
	v_mov_b32_e32 v114, v110
	s_waitcnt lgkmcnt(0)
	v_add_f32_e32 v64, v64, v78
	v_fmamk_f32 v64, v64, 0x3a800000, v169
	v_mul_f32_e32 v78, 0x4b800000, v64
	v_cmp_gt_f32_e32 vcc, s74, v64
	s_nop 1
	v_cndmask_b32_e32 v64, v64, v78, vcc
	v_rsq_f32_e32 v64, v64
	v_mov_b32_e32 v78, v119
	v_mul_f32_e32 v110, 0x45800000, v64
	v_cndmask_b32_e32 v64, v64, v110, vcc
	v_pk_mul_f32 v[110:111], v[80:81], v[64:65] op_sel_hi:[1,0]
	v_pk_mul_f32 v[80:81], v[124:125], v[64:65] op_sel_hi:[1,0]
	v_pk_mul_f32 v[116:117], v[116:117], v[64:65] op_sel_hi:[1,0]
	v_pk_mul_f32 v[118:119], v[78:79], v[64:65] op_sel_hi:[1,0]
	v_pk_mul_f32 v[114:115], v[114:115], v[64:65] op_sel_hi:[1,0]
	v_pk_mul_f32 v[122:123], v[126:127], v[64:65] op_sel_hi:[1,0]
	v_pk_mul_f32 v[120:121], v[120:121], v[64:65] op_sel_hi:[1,0]
	v_pk_mul_f32 v[112:113], v[112:113], v[64:65] op_sel_hi:[1,0]
	s_waitcnt vmcnt(5)
	v_pk_fma_f32 v[80:81], v[68:69], v[80:81], v[76:77]
	v_pk_fma_f32 v[78:79], v[66:67], v[110:111], v[74:75]
	s_waitcnt vmcnt(4)
	v_pk_fma_f32 v[76:77], v[72:73], v[118:119], v[92:93]
	v_pk_fma_f32 v[74:75], v[70:71], v[116:117], v[90:91]
	s_waitcnt vmcnt(1)
	v_pk_fma_f32 v[72:73], v[96:97], v[122:123], v[104:105]
	v_pk_fma_f32 v[70:71], v[94:95], v[114:115], v[102:103]
	s_waitcnt vmcnt(0)
	v_pk_fma_f32 v[68:69], v[100:101], v[112:113], v[108:109]
	v_pk_fma_f32 v[66:67], v[98:99], v[120:121], v[106:107]
	v_mov_b32_e32 v90, 1.0
	s_waitcnt vmcnt(3)
	v_pk_mul_f32 v[90:91], v[78:79], v[78:79]
	s_waitcnt vmcnt(2)
	v_pk_mul_f32 v[92:93], v[74:75], v[74:75]
	v_pk_mul_f32 v[94:95], v[80:81], v[80:81]
	v_pk_mul_f32 v[96:97], v[76:77], v[76:77]
	v_mov_b32_e32 v98, v95
	v_mov_b32_e32 v99, v97
	v_mov_b32_e32 v95, v96
	v_mov_b32_e32 v96, v90
	v_mov_b32_e32 v97, v92
	v_mov_b32_e32 v92, v91
	v_pk_add_f32 v[90:91], v[96:97], v[92:93]
	s_waitcnt vmcnt(0)
	v_mov_b32_e32 v96, v66
	v_pk_add_f32 v[90:91], v[94:95], v[90:91]
	v_mov_b32_e32 v97, v70
	v_pk_add_f32 v[90:91], v[98:99], v[90:91]
	v_mov_b32_e32 v98, v67
	v_mov_b32_e32 v99, v71
	v_pk_mul_f32 v[98:99], v[98:99], v[98:99]
	v_mov_b32_e32 v94, v68
	v_mov_b32_e32 v95, v72
	v_pk_fma_f32 v[96:97], v[96:97], v[96:97], v[98:99]
	v_mov_b32_e32 v92, v69
	v_mov_b32_e32 v93, v73
	v_pk_fma_f32 v[94:95], v[94:95], v[94:95], v[96:97]
	v_add_f32_e32 v64, v90, v91
	v_pk_fma_f32 v[92:93], v[92:93], v[92:93], v[94:95]
	s_nop 0
	v_add_f32_e32 v64, v93, v64
	v_add_f32_e32 v64, v92, v64
	ds_bpermute_b32 v90, v163, v64
	s_waitcnt lgkmcnt(0)
	v_add_f32_e32 v64, v64, v90
	ds_bpermute_b32 v90, v164, v64
	s_waitcnt lgkmcnt(0)
	v_add_f32_e32 v64, v64, v90
	ds_bpermute_b32 v90, v165, v64
	s_waitcnt lgkmcnt(0)
	v_add_f32_e32 v64, v64, v90
	ds_bpermute_b32 v90, v166, v64
	s_waitcnt lgkmcnt(0)
	v_add_f32_e32 v64, v64, v90
	ds_bpermute_b32 v90, v167, v64
	s_waitcnt lgkmcnt(0)
	v_add_f32_e32 v64, v64, v90
	ds_bpermute_b32 v90, v168, v64
	s_waitcnt lgkmcnt(0)
	v_add_f32_e32 v64, v64, v90
	v_fmamk_f32 v64, v64, 0x3a800000, v169
	v_mul_f32_e32 v90, 0x4b800000, v64
	v_cmp_gt_f32_e32 vcc, s74, v64
	s_nop 1
	v_cndmask_b32_e32 v64, v64, v90, vcc
	v_rsq_f32_e32 v64, v64
	s_nop 0
	v_mul_f32_e32 v90, 0x45800000, v64
	v_cndmask_b32_e32 v90, v64, v90, vcc
	v_mov_b32_e32 v91, v90
	s_waitcnt vmcnt(3)
	global_store_dwordx4 v[134:135], v[78:81], off offset:-3072 nt
	s_waitcnt vmcnt(3)
	global_store_dwordx4 v[134:135], v[74:77], off offset:-2048 nt
	s_waitcnt vmcnt(3)
	global_store_dwordx4 v[134:135], v[70:73], off offset:-1024 nt
	s_waitcnt vmcnt(2)
	global_store_dwordx4 v[134:135], v[66:69], off nt
	s_branch .LBB0_150
